# rstd tables: own 256-row panel only, staged into the idle LDS ring by coalesced LDS-DMA and reduced with the original code (P4, P10, P17; P6 own-panel only); plus accumulator-zeroing peel and SWA prol
# speedup vs baseline: 1.0122x; 1.0022x over previous
.LBB0_462:
	s_ashr_i32 s2, s2, 3
	s_add_i32 s2, s9, s2
	s_ashr_i32 s4, s2, 31
	s_lshr_b32 s4, s4, 26
	s_add_i32 s4, s2, s4
	s_and_b32 s5, s4, 0xffc0
	s_sub_i32 s2, s2, s5
	s_bfe_i32 s5, s2, 0x80000
	s_bfe_u32 s5, s5, 0x2000d
	s_add_i32 s5, s2, s5
	s_and_b32 s5, s5, 0xfc
	s_sub_i32 s2, s2, s5
	s_sext_i32_i8 s2, s2
	s_lshl_b32 s4, s4, 4
	s_and_b32 s4, s4, 0xfffffc00
	s_lshl_b32 s2, s2, 8
	s_add_i32 s4, s4, s2
	s_and_b32 s57, s4, 0xfffffc00
	s_bfe_u32 s98, s4, 0x20008
	v_add_u32_e32 v2, 0, v162
	s_ashr_i32 s2, s57, 31
	v_add_u32_e32 v5, 0x20000, v2
	v_or_b32_e32 v2, s57, v0
	s_waitcnt lgkmcnt(0)
	v_mov_b32_e32 v3, s2
	v_lshlrev_b64 v[2:3], 8, v[2:3]
	v_lshl_add_u64 v[2:3], s[18:19], 0, v[2:3]
	s_mov_b64 s[4:5], 0x425000f0
	v_or_b32_e32 v4, 0xfffffe00, v0
	v_lshl_add_u64 v[2:3], v[2:3], 0, s[4:5]
	s_mov_b64 s[8:9], 0
	v_mov_b32_e32 v6, 0x358637bd
	s_mov_b32 s2, 0xf800000
	v_mov_b32_e32 v7, 0x260
	s_mov_b64 s[10:11], 0x20000
	v_readfirstlane_b32 s99, v0
	s_nop 3
	s_lshr_b32 s99, s99, 6
	s_lshl_b32 s100, s98, 8
	s_add_i32 s100, s100, s57
	s_lshl_b32 s100, s100, 8
	s_lshl_b32 s101, s99, 13
	s_add_i32 s100, s100, s101
	v_and_b32_e32 v252, 63, v0
	v_lshlrev_b32_e32 v252, 4, v252
	v_add_u32_e32 v252, s100, v252
	s_add_u32 s100, s18, 0x42500000
	s_addc_u32 s101, s19, 0
	s_mul_i32 m0, s99, 0x2080
	s_nop 0
	global_load_lds_dwordx4 v252, s[100:101]
	v_add_u32_e32 v252, 0x400, v252
	s_add_i32 m0, m0, 0x410
	s_nop 0
	global_load_lds_dwordx4 v252, s[100:101]
	v_add_u32_e32 v252, 0x400, v252
	s_add_i32 m0, m0, 0x410
	s_nop 0
	global_load_lds_dwordx4 v252, s[100:101]
	v_add_u32_e32 v252, 0x400, v252
	s_add_i32 m0, m0, 0x410
	s_nop 0
	global_load_lds_dwordx4 v252, s[100:101]
	v_add_u32_e32 v252, 0x400, v252
	s_add_i32 m0, m0, 0x410
	s_nop 0
	global_load_lds_dwordx4 v252, s[100:101]
	v_add_u32_e32 v252, 0x400, v252
	s_add_i32 m0, m0, 0x410
	s_nop 0
	global_load_lds_dwordx4 v252, s[100:101]
	v_add_u32_e32 v252, 0x400, v252
	s_add_i32 m0, m0, 0x410
	s_nop 0
	global_load_lds_dwordx4 v252, s[100:101]
	v_add_u32_e32 v252, 0x400, v252
	s_add_i32 m0, m0, 0x410
	s_nop 0
	global_load_lds_dwordx4 v252, s[100:101]
	s_waitcnt vmcnt(0)
	s_barrier
	s_cmp_ge_u32 s99, 4
	s_cbranch_scc1 .Ltabdskip_0
	v_lshrrev_b32_e32 v253, 2, v0
	v_mul_u32_u24_e32 v253, 0x410, v253
	v_and_b32_e32 v254, 3, v0
	v_lshl_add_u32 v253, v254, 8, v253
	s_lshl_b32 s100, s98, 10
	v_add_u32_e32 v5, s100, v5
	v_mov_b32_e32 v4, v0
.LBB0_463:
	ds_read_b128 v[8:11], v253 offset:0
	ds_read_b128 v[12:15], v253 offset:16
	ds_read_b128 v[16:19], v253 offset:32
	ds_read_b128 v[20:23], v253 offset:48
	ds_read_b128 v[24:27], v253 offset:64
	ds_read_b128 v[28:31], v253 offset:80
	ds_read_b128 v[32:35], v253 offset:96
	ds_read_b128 v[36:39], v253 offset:112
	ds_read_b128 v[40:43], v253 offset:128
	ds_read_b128 v[44:47], v253 offset:144
	ds_read_b128 v[48:51], v253 offset:160
	ds_read_b128 v[52:55], v253 offset:176
	ds_read_b128 v[56:59], v253 offset:192
	ds_read_b128 v[60:63], v253 offset:208
	ds_read_b128 v[64:67], v253 offset:224
	ds_read_b128 v[68:71], v253 offset:240
	v_lshl_add_u64 v[2:3], v[2:3], 0, s[10:11]
	s_waitcnt lgkmcnt(14)
	v_pk_add_f32 v[10:11], v[10:11], v[14:15]
	v_pk_add_f32 v[8:9], v[8:9], v[12:13]
	s_waitcnt lgkmcnt(13)
	v_pk_add_f32 v[10:11], v[10:11], v[18:19]
	v_pk_add_f32 v[8:9], v[8:9], v[16:17]
	s_waitcnt lgkmcnt(12)
	v_pk_add_f32 v[10:11], v[10:11], v[22:23]
	v_pk_add_f32 v[8:9], v[8:9], v[20:21]
	s_waitcnt lgkmcnt(11)
	v_pk_add_f32 v[10:11], v[10:11], v[26:27]
	v_pk_add_f32 v[8:9], v[8:9], v[24:25]
	s_waitcnt lgkmcnt(10)
	v_pk_add_f32 v[10:11], v[10:11], v[30:31]
	v_pk_add_f32 v[8:9], v[8:9], v[28:29]
	s_waitcnt lgkmcnt(9)
	v_pk_add_f32 v[10:11], v[10:11], v[34:35]
	v_pk_add_f32 v[8:9], v[8:9], v[32:33]
	s_waitcnt lgkmcnt(8)
	v_pk_add_f32 v[10:11], v[10:11], v[38:39]
	v_pk_add_f32 v[8:9], v[8:9], v[36:37]
	s_waitcnt lgkmcnt(7)
	v_pk_add_f32 v[10:11], v[10:11], v[42:43]
	v_pk_add_f32 v[8:9], v[8:9], v[40:41]
	s_waitcnt lgkmcnt(6)
	v_pk_add_f32 v[10:11], v[10:11], v[46:47]
	v_pk_add_f32 v[8:9], v[8:9], v[44:45]
	s_waitcnt lgkmcnt(5)
	v_pk_add_f32 v[10:11], v[10:11], v[50:51]
	v_pk_add_f32 v[8:9], v[8:9], v[48:49]
	s_waitcnt lgkmcnt(4)
	v_pk_add_f32 v[10:11], v[10:11], v[54:55]
	v_pk_add_f32 v[8:9], v[8:9], v[52:53]
	s_waitcnt lgkmcnt(3)
	v_pk_add_f32 v[10:11], v[10:11], v[58:59]
	v_pk_add_f32 v[8:9], v[8:9], v[56:57]
	s_waitcnt lgkmcnt(2)
	v_pk_add_f32 v[10:11], v[10:11], v[62:63]
	v_pk_add_f32 v[8:9], v[8:9], v[60:61]
	s_waitcnt lgkmcnt(1)
	v_pk_add_f32 v[10:11], v[10:11], v[66:67]
	v_pk_add_f32 v[8:9], v[8:9], v[64:65]
	s_waitcnt lgkmcnt(0)
	v_pk_add_f32 v[10:11], v[10:11], v[70:71]
	v_pk_add_f32 v[8:9], v[8:9], v[68:69]
	s_nop 0
	v_pk_mov_b32 v[12:13], v[8:9], v[10:11] op_sel:[1,0]
	v_mov_b32_e32 v9, v11
	v_pk_add_f32 v[8:9], v[12:13], v[8:9]
	s_nop 0
	v_add_f32_e32 v8, v8, v9
	v_fmamk_f32 v8, v8, 0x39800000, v6
	v_mul_f32_e32 v9, 0x4f800000, v8
	v_cmp_gt_f32_e32 vcc, s2, v8
	s_nop 1
	v_cndmask_b32_e32 v8, v8, v9, vcc
	v_sqrt_f32_e32 v9, v8
	s_nop 0
	v_add_u32_e32 v10, -1, v9
	v_add_u32_e32 v11, 1, v9
	v_fma_f32 v12, -v10, v9, v8
	v_fma_f32 v13, -v11, v9, v8
	v_cmp_ge_f32_e64 s[4:5], 0, v12
	s_nop 1
	v_cndmask_b32_e64 v9, v9, v10, s[4:5]
	v_cmp_lt_f32_e64 s[4:5], 0, v13
	s_nop 1
	v_cndmask_b32_e64 v9, v9, v11, s[4:5]
	v_mul_f32_e32 v10, 0x37800000, v9
	v_cndmask_b32_e32 v9, v9, v10, vcc
	v_cmp_class_f32_e32 vcc, v8, v7
	s_nop 1
	v_cndmask_b32_e32 v8, v9, v8, vcc
	v_div_scale_f32 v9, s[4:5], v8, v8, 1.0
	v_rcp_f32_e32 v11, v9
	v_div_scale_f32 v10, vcc, 1.0, v8, 1.0
	v_fma_f32 v12, -v9, v11, 1.0
	v_fmac_f32_e32 v11, v12, v11
	v_mul_f32_e32 v12, v10, v11
	v_fma_f32 v13, -v9, v12, v10
	v_fmac_f32_e32 v12, v13, v11
	v_fma_f32 v9, -v9, v12, v10
	v_div_fmas_f32 v9, v9, v11, v12
	v_add_co_u32_e32 v4, vcc, 0x200, v4
	s_xor_b64 s[4:5], vcc, -1
	v_div_fixup_f32 v8, v9, v8, 1.0
	s_and_b64 s[4:5], exec, s[4:5]
	ds_write_b32 v5, v8
	s_or_b64 s[8:9], s[4:5], s[8:9]
	v_add_u32_e32 v5, 0x800, v5
	s_andn2_b64 exec, exec, s[8:9]
	s_cbranch_execnz .LBB0_463

.LBB0_1357:
	s_ashr_i32 s2, s2, 3
	s_add_i32 s2, s9, s2
	s_ashr_i32 s4, s2, 31
	s_lshr_b32 s4, s4, 26
	s_add_i32 s4, s2, s4
	s_and_b32 s5, s4, 0xffc0
	s_sub_i32 s2, s2, s5
	s_bfe_i32 s5, s2, 0x80000
	s_bfe_u32 s5, s5, 0x2000d
	s_add_i32 s5, s2, s5
	s_and_b32 s5, s5, 0xfc
	s_sub_i32 s2, s2, s5
	s_sext_i32_i8 s2, s2
	s_lshl_b32 s4, s4, 4
	s_and_b32 s4, s4, 0xfffffc00
	s_lshl_b32 s2, s2, 8
	s_add_i32 s4, s4, s2
	s_and_b32 s2, s4, 0xfffffc00
	s_bfe_u32 s98, s4, 0x20008
	v_or_b32_e32 v2, s2, v0
	v_ashrrev_i32_e32 v3, 31, v2
	s_waitcnt vmcnt(0)
	v_add_u32_e32 v8, 0, v162
	v_lshlrev_b64 v[2:3], 8, v[2:3]
	v_or_b32_e32 v6, 0xfffffe00, v0
	v_add_u32_e32 v7, 0x20000, v8
	v_lshl_add_u64 v[2:3], s[18:19], 0, v[2:3]
	s_mov_b64 s[4:5], 0x42b00030
	v_lshl_add_u64 v[4:5], v[2:3], 0, s[4:5]
	s_mov_b64 s[24:25], 0
	v_mov_b32_e32 v9, 0x358637bd
	s_mov_b32 s8, 0xf800000
	v_mov_b32_e32 v10, 0x260
	s_mov_b64 s[30:31], 0x20000
	v_mov_b32_e32 v11, v7
	v_mov_b32_e32 v12, v6
	v_readfirstlane_b32 s99, v0
	s_nop 3
	s_lshr_b32 s99, s99, 6
	s_lshl_b32 s100, s98, 8
	s_add_i32 s100, s100, s2
	s_lshl_b32 s100, s100, 8
	s_lshl_b32 s101, s99, 13
	s_add_i32 s100, s100, s101
	v_and_b32_e32 v252, 63, v0
	v_lshlrev_b32_e32 v252, 4, v252
	v_add_u32_e32 v252, s100, v252
	s_add_u32 s100, s18, 0x42b00000
	s_addc_u32 s101, s19, 0
	s_mul_i32 m0, s99, 0x2080
	s_nop 0
	global_load_lds_dwordx4 v252, s[100:101]
	v_add_u32_e32 v252, 0x400, v252
	s_add_i32 m0, m0, 0x410
	s_nop 0
	global_load_lds_dwordx4 v252, s[100:101]
	v_add_u32_e32 v252, 0x400, v252
	s_add_i32 m0, m0, 0x410
	s_nop 0
	global_load_lds_dwordx4 v252, s[100:101]
	v_add_u32_e32 v252, 0x400, v252
	s_add_i32 m0, m0, 0x410
	s_nop 0
	global_load_lds_dwordx4 v252, s[100:101]
	v_add_u32_e32 v252, 0x400, v252
	s_add_i32 m0, m0, 0x410
	s_nop 0
	global_load_lds_dwordx4 v252, s[100:101]
	v_add_u32_e32 v252, 0x400, v252
	s_add_i32 m0, m0, 0x410
	s_nop 0
	global_load_lds_dwordx4 v252, s[100:101]
	v_add_u32_e32 v252, 0x400, v252
	s_add_i32 m0, m0, 0x410
	s_nop 0
	global_load_lds_dwordx4 v252, s[100:101]
	v_add_u32_e32 v252, 0x400, v252
	s_add_i32 m0, m0, 0x410
	s_nop 0
	global_load_lds_dwordx4 v252, s[100:101]
	s_waitcnt vmcnt(0)
	s_barrier
	s_cmp_ge_u32 s99, 4
	s_cbranch_scc1 .Ltabdskip_2
	v_lshrrev_b32_e32 v253, 2, v0
	v_mul_u32_u24_e32 v253, 0x410, v253
	v_and_b32_e32 v254, 3, v0
	v_lshl_add_u32 v253, v254, 8, v253
	s_lshl_b32 s100, s98, 10
	v_add_u32_e32 v11, s100, v11
	v_mov_b32_e32 v12, v0
.LBB0_1358:
	ds_read_b128 v[14:17], v253 offset:0
	ds_read_b128 v[18:21], v253 offset:16
	ds_read_b128 v[22:25], v253 offset:32
	ds_read_b128 v[26:29], v253 offset:48
	v_lshl_add_u64 v[4:5], v[4:5], 0, s[30:31]
	s_waitcnt lgkmcnt(2)
	v_pk_add_f32 v[16:17], v[16:17], v[20:21]
	v_pk_add_f32 v[14:15], v[14:15], v[18:19]
	s_waitcnt lgkmcnt(1)
	v_pk_add_f32 v[16:17], v[16:17], v[24:25]
	v_pk_add_f32 v[14:15], v[14:15], v[22:23]
	s_waitcnt lgkmcnt(0)
	v_pk_add_f32 v[16:17], v[16:17], v[28:29]
	v_pk_add_f32 v[14:15], v[14:15], v[26:27]
	s_nop 0
	v_pk_mov_b32 v[18:19], v[14:15], v[16:17] op_sel:[1,0]
	v_mov_b32_e32 v15, v17
	v_pk_add_f32 v[14:15], v[18:19], v[14:15]
	s_nop 0
	v_add_f32_e32 v13, v14, v15
	v_fmamk_f32 v13, v13, 0x3a000000, v9
	v_mul_f32_e32 v14, 0x4f800000, v13
	v_cmp_gt_f32_e32 vcc, s8, v13
	s_nop 1
	v_cndmask_b32_e32 v13, v13, v14, vcc
	v_sqrt_f32_e32 v14, v13
	s_nop 0
	v_add_u32_e32 v15, -1, v14
	v_add_u32_e32 v16, 1, v14
	v_fma_f32 v17, -v15, v14, v13
	v_fma_f32 v18, -v16, v14, v13
	v_cmp_ge_f32_e64 s[4:5], 0, v17
	s_nop 1
	v_cndmask_b32_e64 v14, v14, v15, s[4:5]
	v_cmp_lt_f32_e64 s[4:5], 0, v18
	s_nop 1
	v_cndmask_b32_e64 v14, v14, v16, s[4:5]
	v_mul_f32_e32 v15, 0x37800000, v14
	v_cndmask_b32_e32 v14, v14, v15, vcc
	v_cmp_class_f32_e32 vcc, v13, v10
	s_nop 1
	v_cndmask_b32_e32 v13, v14, v13, vcc
	v_div_scale_f32 v14, s[4:5], v13, v13, 1.0
	v_rcp_f32_e32 v16, v14
	v_div_scale_f32 v15, vcc, 1.0, v13, 1.0
	v_fma_f32 v17, -v14, v16, 1.0
	v_fmac_f32_e32 v16, v17, v16
	v_mul_f32_e32 v17, v15, v16
	v_fma_f32 v18, -v14, v17, v15
	v_fmac_f32_e32 v17, v18, v16
	v_fma_f32 v14, -v14, v17, v15
	v_div_fmas_f32 v14, v14, v16, v17
	v_add_co_u32_e32 v12, vcc, 0x200, v12
	s_xor_b64 s[4:5], vcc, -1
	v_div_fixup_f32 v13, v14, v13, 1.0
	s_and_b64 s[4:5], exec, s[4:5]
	ds_write_b32 v11, v13
	s_or_b64 s[24:25], s[4:5], s[24:25]
	v_add_u32_e32 v11, 0x800, v11
	s_andn2_b64 exec, exec, s[24:25]
	s_cbranch_execnz .LBB0_1358
.Ltabdskip_2:
	s_or_b64 exec, exec, s[24:25]
	s_mov_b64 s[4:5], 0x42b000b0
	v_add_u32_e32 v4, 0x21000, v8
	v_lshl_add_u64 v[2:3], v[2:3], 0, s[4:5]
	s_mov_b64 s[24:25], 0
	v_mov_b32_e32 v5, 0x358637bd
	s_mov_b32 s8, 0xf800000
	v_mov_b32_e32 v8, 0x260
	s_mov_b64 s[30:31], 0x20000
	v_mov_b32_e32 v9, v6
	s_waitcnt lgkmcnt(0)
	s_barrier
	v_readfirstlane_b32 s99, v0
	s_nop 3
	s_lshr_b32 s99, s99, 6
	s_cmp_ge_u32 s99, 4
	s_cbranch_scc1 .Ltabdskip_3
	v_lshrrev_b32_e32 v253, 2, v0
	v_mul_u32_u24_e32 v253, 0x410, v253
	v_and_b32_e32 v254, 3, v0
	v_lshl_add_u32 v253, v254, 8, v253
	s_lshl_b32 s100, s98, 10
	v_add_u32_e32 v4, s100, v4
	v_mov_b32_e32 v9, v0
.LBB0_1360:
	ds_read_b128 v[10:13], v253 offset:64
	ds_read_b128 v[14:17], v253 offset:80
	ds_read_b128 v[18:21], v253 offset:96
	ds_read_b128 v[22:25], v253 offset:112
	ds_read_b128 v[26:29], v253 offset:128
	ds_read_b128 v[30:33], v253 offset:144
	ds_read_b128 v[34:37], v253 offset:160
	ds_read_b128 v[38:41], v253 offset:176
	v_lshl_add_u64 v[2:3], v[2:3], 0, s[30:31]
	s_waitcnt lgkmcnt(6)
	v_pk_add_f32 v[12:13], v[12:13], v[16:17]
	v_pk_add_f32 v[10:11], v[10:11], v[14:15]
	s_waitcnt lgkmcnt(5)
	v_pk_add_f32 v[12:13], v[12:13], v[20:21]
	v_pk_add_f32 v[10:11], v[10:11], v[18:19]
	s_waitcnt lgkmcnt(4)
	v_pk_add_f32 v[12:13], v[12:13], v[24:25]
	v_pk_add_f32 v[10:11], v[10:11], v[22:23]
	s_waitcnt lgkmcnt(3)
	v_pk_add_f32 v[12:13], v[12:13], v[28:29]
	v_pk_add_f32 v[10:11], v[10:11], v[26:27]
	s_waitcnt lgkmcnt(2)
	v_pk_add_f32 v[12:13], v[12:13], v[32:33]
	v_pk_add_f32 v[10:11], v[10:11], v[30:31]
	s_waitcnt lgkmcnt(1)
	v_pk_add_f32 v[12:13], v[12:13], v[36:37]
	v_pk_add_f32 v[10:11], v[10:11], v[34:35]
	s_waitcnt lgkmcnt(0)
	v_pk_add_f32 v[12:13], v[12:13], v[40:41]
	v_pk_add_f32 v[10:11], v[10:11], v[38:39]
	s_nop 0
	v_pk_mov_b32 v[14:15], v[10:11], v[12:13] op_sel:[1,0]
	v_mov_b32_e32 v11, v13
	v_pk_add_f32 v[10:11], v[14:15], v[10:11]
	s_nop 0
	v_add_f32_e32 v10, v10, v11
	v_fmamk_f32 v10, v10, 0x3a000000, v5
	v_mul_f32_e32 v11, 0x4f800000, v10
	v_cmp_gt_f32_e32 vcc, s8, v10
	s_nop 1
	v_cndmask_b32_e32 v10, v10, v11, vcc
	v_sqrt_f32_e32 v11, v10
	s_nop 0
	v_add_u32_e32 v12, -1, v11
	v_add_u32_e32 v13, 1, v11
	v_fma_f32 v14, -v12, v11, v10
	v_fma_f32 v15, -v13, v11, v10
	v_cmp_ge_f32_e64 s[4:5], 0, v14
	s_nop 1
	v_cndmask_b32_e64 v11, v11, v12, s[4:5]
	v_cmp_lt_f32_e64 s[4:5], 0, v15
	s_nop 1
	v_cndmask_b32_e64 v11, v11, v13, s[4:5]
	v_mul_f32_e32 v12, 0x37800000, v11
	v_cndmask_b32_e32 v11, v11, v12, vcc
	v_cmp_class_f32_e32 vcc, v10, v8
	s_nop 1
	v_cndmask_b32_e32 v10, v11, v10, vcc
	v_div_scale_f32 v11, s[4:5], v10, v10, 1.0
	v_rcp_f32_e32 v13, v11
	v_div_scale_f32 v12, vcc, 1.0, v10, 1.0
	v_fma_f32 v14, -v11, v13, 1.0
	v_fmac_f32_e32 v13, v14, v13
	v_mul_f32_e32 v14, v12, v13
	v_fma_f32 v15, -v11, v14, v12
	v_fmac_f32_e32 v14, v15, v13
	v_fma_f32 v11, -v11, v14, v12
	v_div_fmas_f32 v11, v11, v13, v14
	v_add_co_u32_e32 v9, vcc, 0x200, v9
	s_xor_b64 s[4:5], vcc, -1
	v_div_fixup_f32 v10, v11, v10, 1.0
	s_and_b64 s[4:5], exec, s[4:5]
	ds_write_b32 v4, v10
	s_or_b64 s[24:25], s[4:5], s[24:25]
	v_add_u32_e32 v4, 0x800, v4
	s_andn2_b64 exec, exec, s[24:25]
	s_cbranch_execnz .LBB0_1360

.LBB0_2157:
	s_cmp_lt_i32 s92, 18
	s_cselect_b64 s[4:5], -1, 0
	s_cmp_gt_i32 s93, 17
	s_cselect_b64 s[6:7], -1, 0
	s_and_b64 s[6:7], s[4:5], s[6:7]
	s_andn2_b64 vcc, exec, s[6:7]
	s_cbranch_vccnz .LBB0_2324
	s_cmpk_lt_i32 s96, 0xac0
	s_cselect_b64 s[8:9], -1, 0
	s_cmpk_gt_i32 s96, 0xabf
	s_mov_b32 s2, 0
	s_cbranch_scc1 .LBB0_2162
	s_ashr_i32 s2, s96, 31
	s_lshr_b32 s2, s2, 29
	s_add_i32 s2, s96, s2
	s_ashr_i32 s4, s2, 3
	s_and_b32 s2, s2, -8
	s_sub_i32 s2, s96, s2
	s_cmp_lt_i32 s2, 0
	s_movk_i32 s5, 0x159
	s_cselect_b32 s5, s5, 0x158
	s_mul_i32 s2, s2, s5
	s_add_i32 s2, s2, s4
	s_mul_hi_i32 s4, s2, 0x2fa0be83
	s_lshr_b32 s5, s4, 31
	s_ashr_i32 s4, s4, 6
	s_add_i32 s4, s4, s5
	s_mul_i32 s5, s4, 0x158
	s_sub_i32 s2, s2, s5
	s_bfe_u32 s5, s2, 0x2001d
	s_add_i32 s5, s2, s5
	s_and_b32 s5, s5, 0xfffc
	s_sub_i32 s2, s2, s5
	s_sext_i32_i16 s2, s2
	s_lshl_b32 s4, s4, 10
	s_lshl_b32 s2, s2, 8
	s_add_i32 s4, s4, s2
	s_and_b32 s2, s4, 0xfffffc00
	s_bfe_u32 s98, s4, 0x20008
	v_add_u32_e32 v2, 0, v162
	s_ashr_i32 s4, s2, 31
	v_add_u32_e32 v5, 0x20000, v2
	v_or_b32_e32 v2, s2, v0
	v_mov_b32_e32 v3, s4
	v_lshlrev_b64 v[2:3], 8, v[2:3]
	v_lshl_add_u64 v[2:3], s[18:19], 0, v[2:3]
	s_mov_b64 s[4:5], 0x429000f0
	v_or_b32_e32 v4, 0xfffffe00, v0
	v_lshl_add_u64 v[2:3], v[2:3], 0, s[4:5]
	s_mov_b64 s[22:23], 0
	s_waitcnt vmcnt(0)
	v_mov_b32_e32 v6, 0x358637bd
	s_mov_b32 s14, 0xf800000
	v_mov_b32_e32 v7, 0x260
	s_mov_b64 s[24:25], 0x20000
	v_readfirstlane_b32 s99, v0
	s_nop 3
	s_lshr_b32 s99, s99, 6
	s_lshl_b32 s100, s98, 8
	s_add_i32 s100, s100, s2
	s_lshl_b32 s100, s100, 8
	s_lshl_b32 s101, s99, 13
	s_add_i32 s100, s100, s101
	v_and_b32_e32 v252, 63, v0
	v_lshlrev_b32_e32 v252, 4, v252
	v_add_u32_e32 v252, s100, v252
	s_add_u32 s100, s18, 0x42900000
	s_addc_u32 s101, s19, 0
	s_mul_i32 m0, s99, 0x2080
	s_nop 0
	global_load_lds_dwordx4 v252, s[100:101]
	v_add_u32_e32 v252, 0x400, v252
	s_add_i32 m0, m0, 0x410
	s_nop 0
	global_load_lds_dwordx4 v252, s[100:101]
	v_add_u32_e32 v252, 0x400, v252
	s_add_i32 m0, m0, 0x410
	s_nop 0
	global_load_lds_dwordx4 v252, s[100:101]
	v_add_u32_e32 v252, 0x400, v252
	s_add_i32 m0, m0, 0x410
	s_nop 0
	global_load_lds_dwordx4 v252, s[100:101]
	v_add_u32_e32 v252, 0x400, v252
	s_add_i32 m0, m0, 0x410
	s_nop 0
	global_load_lds_dwordx4 v252, s[100:101]
	v_add_u32_e32 v252, 0x400, v252
	s_add_i32 m0, m0, 0x410
	s_nop 0
	global_load_lds_dwordx4 v252, s[100:101]
	v_add_u32_e32 v252, 0x400, v252
	s_add_i32 m0, m0, 0x410
	s_nop 0
	global_load_lds_dwordx4 v252, s[100:101]
	v_add_u32_e32 v252, 0x400, v252
	s_add_i32 m0, m0, 0x410
	s_nop 0
	global_load_lds_dwordx4 v252, s[100:101]
	s_waitcnt vmcnt(0)
	s_barrier
	s_cmp_ge_u32 s99, 4
	s_cbranch_scc1 .Ltabdskip_1
	v_lshrrev_b32_e32 v253, 2, v0
	v_mul_u32_u24_e32 v253, 0x410, v253
	v_and_b32_e32 v254, 3, v0
	v_lshl_add_u32 v253, v254, 8, v253
	s_lshl_b32 s100, s98, 10
	v_add_u32_e32 v5, s100, v5
	v_mov_b32_e32 v4, v0
.LBB0_2160:
	ds_read_b128 v[8:11], v253 offset:0
	ds_read_b128 v[12:15], v253 offset:16
	ds_read_b128 v[16:19], v253 offset:32
	ds_read_b128 v[20:23], v253 offset:48
	ds_read_b128 v[24:27], v253 offset:64
	ds_read_b128 v[28:31], v253 offset:80
	ds_read_b128 v[32:35], v253 offset:96
	ds_read_b128 v[36:39], v253 offset:112
	ds_read_b128 v[40:43], v253 offset:128
	ds_read_b128 v[44:47], v253 offset:144
	ds_read_b128 v[48:51], v253 offset:160
	ds_read_b128 v[52:55], v253 offset:176
	ds_read_b128 v[56:59], v253 offset:192
	ds_read_b128 v[60:63], v253 offset:208
	ds_read_b128 v[64:67], v253 offset:224
	ds_read_b128 v[68:71], v253 offset:240
	v_lshl_add_u64 v[2:3], v[2:3], 0, s[24:25]
	s_waitcnt lgkmcnt(14)
	v_pk_add_f32 v[10:11], v[10:11], v[14:15]
	v_pk_add_f32 v[8:9], v[8:9], v[12:13]
	s_waitcnt lgkmcnt(13)
	v_pk_add_f32 v[10:11], v[10:11], v[18:19]
	v_pk_add_f32 v[8:9], v[8:9], v[16:17]
	s_waitcnt lgkmcnt(12)
	v_pk_add_f32 v[10:11], v[10:11], v[22:23]
	v_pk_add_f32 v[8:9], v[8:9], v[20:21]
	s_waitcnt lgkmcnt(11)
	v_pk_add_f32 v[10:11], v[10:11], v[26:27]
	v_pk_add_f32 v[8:9], v[8:9], v[24:25]
	s_waitcnt lgkmcnt(10)
	v_pk_add_f32 v[10:11], v[10:11], v[30:31]
	v_pk_add_f32 v[8:9], v[8:9], v[28:29]
	s_waitcnt lgkmcnt(9)
	v_pk_add_f32 v[10:11], v[10:11], v[34:35]
	v_pk_add_f32 v[8:9], v[8:9], v[32:33]
	s_waitcnt lgkmcnt(8)
	v_pk_add_f32 v[10:11], v[10:11], v[38:39]
	v_pk_add_f32 v[8:9], v[8:9], v[36:37]
	s_waitcnt lgkmcnt(7)
	v_pk_add_f32 v[10:11], v[10:11], v[42:43]
	v_pk_add_f32 v[8:9], v[8:9], v[40:41]
	s_waitcnt lgkmcnt(6)
	v_pk_add_f32 v[10:11], v[10:11], v[46:47]
	v_pk_add_f32 v[8:9], v[8:9], v[44:45]
	s_waitcnt lgkmcnt(5)
	v_pk_add_f32 v[10:11], v[10:11], v[50:51]
	v_pk_add_f32 v[8:9], v[8:9], v[48:49]
	s_waitcnt lgkmcnt(4)
	v_pk_add_f32 v[10:11], v[10:11], v[54:55]
	v_pk_add_f32 v[8:9], v[8:9], v[52:53]
	s_waitcnt lgkmcnt(3)
	v_pk_add_f32 v[10:11], v[10:11], v[58:59]
	v_pk_add_f32 v[8:9], v[8:9], v[56:57]
	s_waitcnt lgkmcnt(2)
	v_pk_add_f32 v[10:11], v[10:11], v[62:63]
	v_pk_add_f32 v[8:9], v[8:9], v[60:61]
	s_waitcnt lgkmcnt(1)
	v_pk_add_f32 v[10:11], v[10:11], v[66:67]
	v_pk_add_f32 v[8:9], v[8:9], v[64:65]
	s_waitcnt lgkmcnt(0)
	v_pk_add_f32 v[10:11], v[10:11], v[70:71]
	v_pk_add_f32 v[8:9], v[8:9], v[68:69]
	s_nop 0
	v_pk_mov_b32 v[12:13], v[8:9], v[10:11] op_sel:[1,0]
	v_mov_b32_e32 v9, v11
	v_pk_add_f32 v[8:9], v[12:13], v[8:9]
	s_nop 0
	v_add_f32_e32 v8, v8, v9
	v_fmamk_f32 v8, v8, 0x39800000, v6
	v_mul_f32_e32 v9, 0x4f800000, v8
	v_cmp_gt_f32_e32 vcc, s14, v8
	s_nop 1
	v_cndmask_b32_e32 v8, v8, v9, vcc
	v_sqrt_f32_e32 v9, v8
	s_nop 0
	v_add_u32_e32 v10, -1, v9
	v_add_u32_e32 v11, 1, v9
	v_fma_f32 v12, -v10, v9, v8
	v_fma_f32 v13, -v11, v9, v8
	v_cmp_ge_f32_e64 s[4:5], 0, v12
	s_nop 1
	v_cndmask_b32_e64 v9, v9, v10, s[4:5]
	v_cmp_lt_f32_e64 s[4:5], 0, v13
	s_nop 1
	v_cndmask_b32_e64 v9, v9, v11, s[4:5]
	v_mul_f32_e32 v10, 0x37800000, v9
	v_cndmask_b32_e32 v9, v9, v10, vcc
	v_cmp_class_f32_e32 vcc, v8, v7
	s_nop 1
	v_cndmask_b32_e32 v8, v9, v8, vcc
	v_div_scale_f32 v9, s[4:5], v8, v8, 1.0
	v_rcp_f32_e32 v11, v9
	v_div_scale_f32 v10, vcc, 1.0, v8, 1.0
	v_fma_f32 v12, -v9, v11, 1.0
	v_fmac_f32_e32 v11, v12, v11
	v_mul_f32_e32 v12, v10, v11
	v_fma_f32 v13, -v9, v12, v10
	v_fmac_f32_e32 v12, v13, v11
	v_fma_f32 v9, -v9, v12, v10
	v_div_fmas_f32 v9, v9, v11, v12
	v_add_co_u32_e32 v4, vcc, 0x200, v4
	s_xor_b64 s[4:5], vcc, -1
	v_div_fixup_f32 v8, v9, v8, 1.0
	s_and_b64 s[4:5], exec, s[4:5]
	ds_write_b32 v5, v8
	s_or_b64 s[22:23], s[4:5], s[22:23]
	v_add_u32_e32 v5, 0x800, v5
	s_andn2_b64 exec, exec, s[22:23]
	s_cbranch_execnz .LBB0_2160

	.amdhsa_kernel _Z10fwd_kernel4Args
		.amdhsa_group_segment_fixed_size 0
		.amdhsa_private_segment_fixed_size 0
		.amdhsa_kernarg_size 536
		.amdhsa_user_sgpr_count 2
		.amdhsa_user_sgpr_dispatch_ptr 0
		.amdhsa_user_sgpr_queue_ptr 0
		.amdhsa_user_sgpr_kernarg_segment_ptr 1
		.amdhsa_user_sgpr_dispatch_id 0
		.amdhsa_user_sgpr_kernarg_preload_length 0
		.amdhsa_user_sgpr_kernarg_preload_offset 0
		.amdhsa_user_sgpr_private_segment_size 0
		.amdhsa_uses_dynamic_stack 0
		.amdhsa_enable_private_segment 0
		.amdhsa_system_sgpr_workgroup_id_x 1
		.amdhsa_system_sgpr_workgroup_id_y 0
		.amdhsa_system_sgpr_workgroup_id_z 0
		.amdhsa_system_sgpr_workgroup_info 0
		.amdhsa_system_vgpr_workitem_id 0
		.amdhsa_next_free_vgpr 255
		.amdhsa_next_free_sgpr 102
		.amdhsa_accum_offset 256
		.amdhsa_reserve_vcc 1
		.amdhsa_float_round_mode_32 0
		.amdhsa_float_round_mode_16_64 0
		.amdhsa_float_denorm_mode_32 3
		.amdhsa_float_denorm_mode_16_64 3
		.amdhsa_dx10_clamp 1
		.amdhsa_ieee_mode 1
		.amdhsa_fp16_overflow 0
		.amdhsa_tg_split 0
		.amdhsa_exception_fp_ieee_invalid_op 0
		.amdhsa_exception_fp_denorm_src 0
		.amdhsa_exception_fp_ieee_div_zero 0
		.amdhsa_exception_fp_ieee_overflow 0
		.amdhsa_exception_fp_ieee_underflow 0
		.amdhsa_exception_fp_ieee_inexact 0
		.amdhsa_exception_int_div_zero 0
	.end_amdhsa_kernel

amdhsa.kernels:
  - .agpr_count:     0
    .args:
      - .offset:         0
        .size:           280
        .value_kind:     by_value
      - .offset:         280
        .size:           4
        .value_kind:     hidden_block_count_x
      - .offset:         284
        .size:           4
        .value_kind:     hidden_block_count_y
      - .offset:         288
        .size:           4
        .value_kind:     hidden_block_count_z
      - .offset:         292
        .size:           2
        .value_kind:     hidden_group_size_x
      - .offset:         294
        .size:           2
        .value_kind:     hidden_group_size_y
      - .offset:         296
        .size:           2
        .value_kind:     hidden_group_size_z
      - .offset:         298
        .size:           2
        .value_kind:     hidden_remainder_x
      - .offset:         300
        .size:           2
        .value_kind:     hidden_remainder_y
      - .offset:         302
        .size:           2
        .value_kind:     hidden_remainder_z
      - .offset:         320
        .size:           8
        .value_kind:     hidden_global_offset_x
      - .offset:         328
        .size:           8
        .value_kind:     hidden_global_offset_y
      - .offset:         336
        .size:           8
        .value_kind:     hidden_global_offset_z
      - .offset:         344
        .size:           2
        .value_kind:     hidden_grid_dims
      - .offset:         400
        .size:           4
        .value_kind:     hidden_dynamic_lds_size
    .group_segment_fixed_size: 0
    .kernarg_segment_align: 8
    .kernarg_segment_size: 536
    .language:       OpenCL C
    .language_version:
      - 2
      - 0
    .max_flat_workgroup_size: 512
    .name:           _Z10fwd_kernel4Args
    .private_segment_fixed_size: 0
    .sgpr_count:     108
    .sgpr_spill_count: 58
    .symbol:         _Z10fwd_kernel4Args.kd
    .uniform_work_group_size: 1
    .uses_dynamic_stack: false
    .vgpr_count:     255
    .vgpr_spill_count: 0
    .wavefront_size: 64
